# Up0/Up1 epilogue stores with nt (streaming) cache hint, on v49
# baseline (speedup 1.0000x reference)
; DI unsigned pk_bf16(float a, float b) { f32x2 v = {a, b}; bf2_t r = __builtin_convertvector(v, bf2_t); return __builtin_bit_cast(unsigned, r); }
;     DI void operator()(const pg8::f32x4 (&acc)[2][2][4][2], const pg8::Unit& u, int wr, int wc, int fr, int fq) const {
;     ...
;             for (int m = 0; m < 4; ++m) {
;                 const int row = row0 + ai * 128 + m * 16;
;                 bf16_t* rp = U + (size_t)row * 4096 + col0;
; #pragma unroll
;                 for (int bj = 0; bj < 2; ++bj) {
;                     float v[8];
; #pragma unroll
;                     for (int n = 0; n < 2; ++n)
; #pragma unroll
;                         for (int e = 0; e < 4; ++e) { const float t = fmaxf(acc[ai][bj][m][n][e], 0.f); v[4 * n + e] = t * t; }
;                     u32x4 w; w.x = pk_bf16(v[0], v[1]); w.y = pk_bf16(v[2], v[3]); w.z = pk_bf16(v[4], v[5]); w.w = pk_bf16(v[6], v[7]);
;                     *(u32x4*)(rp + bj * 128) = w;
.LBB0_1475:
	v_lshl_add_u32 v154, s28, 8, v1
	v_lshl_or_b32 v146, s57, 8, v149
	v_ashrrev_i32_e32 v155, 31, v154
	v_ashrrev_i32_e32 v147, 31, v146
	v_lshlrev_b64 v[156:157], 13, v[154:155]
	v_lshl_add_u64 v[156:157], s[66:67], 0, v[156:157]
	v_lshlrev_b64 v[158:159], 1, v[146:147]
	v_max_f32_e32 v122, 0, v122
	v_max_f32_e32 v123, 0, v123
	v_lshl_add_u64 v[146:147], v[156:157], 0, v[158:159]
	v_pk_mul_f32 v[156:157], v[122:123], v[122:123]
	v_max_f32_e32 v126, 0, v126
	v_max_f32_e32 v127, 0, v127
	v_max_f32_e32 v128, 0, v128
	v_max_f32_e32 v129, 0, v129
	v_max_f32_e32 v122, 0, v124
	v_max_f32_e32 v123, 0, v125
	v_pk_mul_f32 v[126:127], v[126:127], v[126:127]
	v_pk_mul_f32 v[128:129], v[128:129], v[128:129]
	v_pk_mul_f32 v[160:161], v[122:123], v[122:123]
	v_cvt_pk_bf16_f32 v122, v126, v127
	v_cvt_pk_bf16_f32 v123, v128, v129
	v_cvt_pk_bf16_f32 v124, v156, v157
	v_cvt_pk_bf16_f32 v125, v160, v161
	v_max_f32_e32 v114, 0, v114
	v_max_f32_e32 v115, 0, v115
	global_store_dwordx4 v[146:147], v[122:125], off nt
	s_nop 1
	v_pk_mul_f32 v[122:123], v[114:115], v[114:115]
	v_max_f32_e32 v118, 0, v118
	v_max_f32_e32 v119, 0, v119
	v_max_f32_e32 v120, 0, v120
	v_max_f32_e32 v121, 0, v121
	v_max_f32_e32 v114, 0, v116
	v_max_f32_e32 v115, 0, v117
	v_pk_mul_f32 v[118:119], v[118:119], v[118:119]
	v_pk_mul_f32 v[120:121], v[120:121], v[120:121]
	v_pk_mul_f32 v[124:125], v[114:115], v[114:115]
	v_cvt_pk_bf16_f32 v114, v118, v119
	v_cvt_pk_bf16_f32 v115, v120, v121
	v_cvt_pk_bf16_f32 v116, v122, v123
	v_cvt_pk_bf16_f32 v117, v124, v125
	global_store_dwordx4 v[146:147], v[114:117], off offset:256 nt
	v_max_f32_e32 v106, 0, v106
	v_max_f32_e32 v107, 0, v107
	v_or_b32_e32 v114, 16, v154
	v_ashrrev_i32_e32 v115, 31, v114
	v_pk_mul_f32 v[116:117], v[106:107], v[106:107]
	v_lshlrev_b64 v[114:115], 13, v[114:115]
	v_max_f32_e32 v110, 0, v110
	v_max_f32_e32 v111, 0, v111
	v_max_f32_e32 v112, 0, v112
	v_max_f32_e32 v113, 0, v113
	v_max_f32_e32 v106, 0, v108
	v_max_f32_e32 v107, 0, v109
	v_lshl_add_u64 v[114:115], s[66:67], 0, v[114:115]
	v_pk_mul_f32 v[110:111], v[110:111], v[110:111]
	v_pk_mul_f32 v[112:113], v[112:113], v[112:113]
	v_pk_mul_f32 v[118:119], v[106:107], v[106:107]
	v_lshl_add_u64 v[114:115], v[114:115], 0, v[158:159]
	v_cvt_pk_bf16_f32 v106, v110, v111
	v_cvt_pk_bf16_f32 v107, v112, v113
	v_cvt_pk_bf16_f32 v108, v116, v117
	v_cvt_pk_bf16_f32 v109, v118, v119
	v_max_f32_e32 v98, 0, v98
	v_max_f32_e32 v99, 0, v99
	global_store_dwordx4 v[114:115], v[106:109], off nt
	s_nop 1
	v_pk_mul_f32 v[106:107], v[98:99], v[98:99]
	v_max_f32_e32 v102, 0, v102
	v_max_f32_e32 v103, 0, v103
	v_max_f32_e32 v104, 0, v104
	v_max_f32_e32 v105, 0, v105
	v_max_f32_e32 v98, 0, v100
	v_max_f32_e32 v99, 0, v101
	v_pk_mul_f32 v[102:103], v[102:103], v[102:103]
	v_pk_mul_f32 v[104:105], v[104:105], v[104:105]
	v_pk_mul_f32 v[108:109], v[98:99], v[98:99]
	v_cvt_pk_bf16_f32 v98, v102, v103
	v_cvt_pk_bf16_f32 v99, v104, v105
	v_cvt_pk_bf16_f32 v100, v106, v107
	v_cvt_pk_bf16_f32 v101, v108, v109
	global_store_dwordx4 v[114:115], v[98:101], off offset:256 nt
	v_max_f32_e32 v90, 0, v90
	v_max_f32_e32 v91, 0, v91
	v_or_b32_e32 v98, 32, v154
	v_ashrrev_i32_e32 v99, 31, v98
	v_pk_mul_f32 v[100:101], v[90:91], v[90:91]
	v_lshlrev_b64 v[98:99], 13, v[98:99]
	v_max_f32_e32 v94, 0, v94
	v_max_f32_e32 v95, 0, v95
	v_max_f32_e32 v96, 0, v96
	v_max_f32_e32 v97, 0, v97
	v_max_f32_e32 v90, 0, v92
	v_max_f32_e32 v91, 0, v93
	v_lshl_add_u64 v[98:99], s[66:67], 0, v[98:99]
	v_pk_mul_f32 v[94:95], v[94:95], v[94:95]
	v_pk_mul_f32 v[96:97], v[96:97], v[96:97]
	v_pk_mul_f32 v[102:103], v[90:91], v[90:91]
	v_lshl_add_u64 v[98:99], v[98:99], 0, v[158:159]
	v_cvt_pk_bf16_f32 v90, v94, v95
	v_cvt_pk_bf16_f32 v91, v96, v97
	v_cvt_pk_bf16_f32 v92, v100, v101
	v_cvt_pk_bf16_f32 v93, v102, v103
	v_max_f32_e32 v82, 0, v82
	v_max_f32_e32 v83, 0, v83
	global_store_dwordx4 v[98:99], v[90:93], off nt
	s_nop 1
	v_pk_mul_f32 v[90:91], v[82:83], v[82:83]
	v_max_f32_e32 v86, 0, v86
	v_max_f32_e32 v87, 0, v87
	v_max_f32_e32 v88, 0, v88
	v_max_f32_e32 v89, 0, v89
	v_max_f32_e32 v82, 0, v84
	v_max_f32_e32 v83, 0, v85
	v_pk_mul_f32 v[86:87], v[86:87], v[86:87]
	v_pk_mul_f32 v[88:89], v[88:89], v[88:89]
	v_pk_mul_f32 v[92:93], v[82:83], v[82:83]
	v_cvt_pk_bf16_f32 v82, v86, v87
	v_cvt_pk_bf16_f32 v83, v88, v89
	v_cvt_pk_bf16_f32 v84, v90, v91
	v_cvt_pk_bf16_f32 v85, v92, v93
	global_store_dwordx4 v[98:99], v[82:85], off offset:256 nt
	v_max_f32_e32 v74, 0, v74
	v_max_f32_e32 v75, 0, v75
	v_or_b32_e32 v82, 48, v154
	v_ashrrev_i32_e32 v83, 31, v82
	v_pk_mul_f32 v[84:85], v[74:75], v[74:75]
	v_lshlrev_b64 v[82:83], 13, v[82:83]
	v_max_f32_e32 v78, 0, v78
	v_max_f32_e32 v79, 0, v79
	v_max_f32_e32 v80, 0, v80
	v_max_f32_e32 v81, 0, v81
	v_max_f32_e32 v74, 0, v76
	v_max_f32_e32 v75, 0, v77
	v_lshl_add_u64 v[82:83], s[66:67], 0, v[82:83]
	v_pk_mul_f32 v[78:79], v[78:79], v[78:79]
	v_pk_mul_f32 v[80:81], v[80:81], v[80:81]
	v_pk_mul_f32 v[86:87], v[74:75], v[74:75]
	v_lshl_add_u64 v[82:83], v[82:83], 0, v[158:159]
	v_cvt_pk_bf16_f32 v74, v78, v79
	v_cvt_pk_bf16_f32 v75, v80, v81
	v_cvt_pk_bf16_f32 v76, v84, v85
	v_cvt_pk_bf16_f32 v77, v86, v87
	v_max_f32_e32 v66, 0, v66
	v_max_f32_e32 v67, 0, v67
	global_store_dwordx4 v[82:83], v[74:77], off nt
	s_nop 1
	v_pk_mul_f32 v[74:75], v[66:67], v[66:67]
	v_max_f32_e32 v70, 0, v70
	v_max_f32_e32 v71, 0, v71
	v_max_f32_e32 v72, 0, v72
	v_max_f32_e32 v73, 0, v73
	v_max_f32_e32 v66, 0, v68
	v_max_f32_e32 v67, 0, v69
	v_pk_mul_f32 v[70:71], v[70:71], v[70:71]
	v_pk_mul_f32 v[72:73], v[72:73], v[72:73]
	v_pk_mul_f32 v[76:77], v[66:67], v[66:67]
	v_cvt_pk_bf16_f32 v66, v70, v71
; DI unsigned pk_bf16(float a, float b) { f32x2 v = {a, b}; bf2_t r = __builtin_convertvector(v, bf2_t); return __builtin_bit_cast(unsigned, r); }
;     DI void operator()(const pg8::f32x4 (&acc)[2][2][4][2], const pg8::Unit& u, int wr, int wc, int fr, int fq) const {
;     ...
;             for (int m = 0; m < 4; ++m) {
;                 const int row = row0 + ai * 128 + m * 16;
;                 bf16_t* rp = U + (size_t)row * 4096 + col0;
; #pragma unroll
;                 for (int bj = 0; bj < 2; ++bj) {
;                     float v[8];
; #pragma unroll
;                     for (int n = 0; n < 2; ++n)
; #pragma unroll
;                         for (int e = 0; e < 4; ++e) { const float t = fmaxf(acc[ai][bj][m][n][e], 0.f); v[4 * n + e] = t * t; }
;                     u32x4 w; w.x = pk_bf16(v[0], v[1]); w.y = pk_bf16(v[2], v[3]); w.z = pk_bf16(v[4], v[5]); w.w = pk_bf16(v[6], v[7]);
;                     *(u32x4*)(rp + bj * 128) = w;
	v_cvt_pk_bf16_f32 v67, v72, v73
	v_cvt_pk_bf16_f32 v68, v74, v75
	v_cvt_pk_bf16_f32 v69, v76, v77
	v_max_f32_e32 v58, 0, v58
	v_max_f32_e32 v59, 0, v59
	global_store_dwordx4 v[82:83], v[66:69], off offset:256 nt
	v_max_f32_e32 v62, 0, v62
	v_max_f32_e32 v63, 0, v63
	v_pk_mul_f32 v[68:69], v[58:59], v[58:59]
	v_pk_mul_f32 v[62:63], v[62:63], v[62:63]
	v_max_f32_e32 v64, 0, v64
	v_max_f32_e32 v65, 0, v65
	v_max_f32_e32 v58, 0, v60
	v_max_f32_e32 v59, 0, v61
	v_pk_mul_f32 v[64:65], v[64:65], v[64:65]
	v_pk_mul_f32 v[70:71], v[58:59], v[58:59]
	v_cvt_pk_bf16_f32 v58, v62, v63
	v_add_co_u32_e32 v62, vcc, s53, v146
	v_cvt_pk_bf16_f32 v59, v64, v65
	v_cvt_pk_bf16_f32 v60, v68, v69
	v_cvt_pk_bf16_f32 v61, v70, v71
	v_addc_co_u32_e32 v63, vcc, 0, v147, vcc
	v_max_f32_e32 v46, 0, v46
	v_max_f32_e32 v47, 0, v47
	global_store_dwordx4 v[62:63], v[58:61], off nt
	s_nop 1
	v_pk_mul_f32 v[58:59], v[46:47], v[46:47]
	v_max_f32_e32 v54, 0, v54
	v_max_f32_e32 v55, 0, v55
	v_max_f32_e32 v56, 0, v56
	v_max_f32_e32 v57, 0, v57
	v_max_f32_e32 v46, 0, v48
	v_max_f32_e32 v47, 0, v49
	v_pk_mul_f32 v[54:55], v[54:55], v[54:55]
	v_pk_mul_f32 v[56:57], v[56:57], v[56:57]
	v_pk_mul_f32 v[60:61], v[46:47], v[46:47]
	v_lshl_add_u64 v[66:67], v[146:147], 0, s[12:13]
	v_cvt_pk_bf16_f32 v46, v54, v55
	v_cvt_pk_bf16_f32 v47, v56, v57
	v_cvt_pk_bf16_f32 v48, v58, v59
	v_cvt_pk_bf16_f32 v49, v60, v61
	global_store_dwordx4 v[66:67], v[46:49], off offset:256 nt
	v_max_f32_e32 v42, 0, v42
	v_max_f32_e32 v43, 0, v43
	v_max_f32_e32 v48, 0, v50
	v_max_f32_e32 v49, 0, v51
	v_max_f32_e32 v50, v52, v52
	v_max_f32_e32 v51, v53, v53
	v_pk_mul_f32 v[52:53], v[42:43], v[42:43]
	v_pk_mul_f32 v[48:49], v[48:49], v[48:49]
	v_max_f32_e32 v50, 0, v50
	v_max_f32_e32 v51, 0, v51
	v_max_f32_e32 v42, 0, v44
	v_max_f32_e32 v43, 0, v45
	v_pk_mul_f32 v[50:51], v[50:51], v[50:51]
	v_pk_mul_f32 v[54:55], v[42:43], v[42:43]
	v_cvt_pk_bf16_f32 v42, v48, v49
	v_add_co_u32_e32 v48, vcc, s54, v146
	v_cvt_pk_bf16_f32 v43, v50, v51
	v_cvt_pk_bf16_f32 v44, v52, v53
	v_cvt_pk_bf16_f32 v45, v54, v55
	v_addc_co_u32_e32 v49, vcc, 0, v147, vcc
	v_max_f32_e32 v30, 0, v30
	v_max_f32_e32 v31, 0, v31
	global_store_dwordx4 v[48:49], v[42:45], off nt
	s_nop 1
	v_pk_mul_f32 v[42:43], v[30:31], v[30:31]
	v_max_f32_e32 v38, 0, v38
	v_max_f32_e32 v39, 0, v39
	v_max_f32_e32 v40, 0, v40
	v_max_f32_e32 v41, 0, v41
	v_max_f32_e32 v30, 0, v32
	v_max_f32_e32 v31, 0, v33
	v_pk_mul_f32 v[38:39], v[38:39], v[38:39]
	v_pk_mul_f32 v[40:41], v[40:41], v[40:41]
	v_pk_mul_f32 v[44:45], v[30:31], v[30:31]
	v_lshl_add_u64 v[46:47], v[146:147], 0, s[14:15]
	v_cvt_pk_bf16_f32 v30, v38, v39
	v_cvt_pk_bf16_f32 v31, v40, v41
	v_cvt_pk_bf16_f32 v32, v42, v43
	v_cvt_pk_bf16_f32 v33, v44, v45
	global_store_dwordx4 v[46:47], v[30:33], off offset:256 nt
	v_max_f32_e32 v26, 0, v26
	v_max_f32_e32 v27, 0, v27
	v_max_f32_e32 v32, 0, v34
	v_max_f32_e32 v33, 0, v35
	v_max_f32_e32 v34, v36, v36
	v_max_f32_e32 v35, v37, v37
	v_pk_mul_f32 v[36:37], v[26:27], v[26:27]
	v_pk_mul_f32 v[32:33], v[32:33], v[32:33]
	v_max_f32_e32 v34, 0, v34
	v_max_f32_e32 v35, 0, v35
	v_max_f32_e32 v26, 0, v28
	v_max_f32_e32 v27, 0, v29
	v_pk_mul_f32 v[34:35], v[34:35], v[34:35]
	v_pk_mul_f32 v[38:39], v[26:27], v[26:27]
	v_cvt_pk_bf16_f32 v26, v32, v33
	v_add_co_u32_e32 v32, vcc, s55, v146
	v_cvt_pk_bf16_f32 v27, v34, v35
	v_cvt_pk_bf16_f32 v28, v36, v37
	v_cvt_pk_bf16_f32 v29, v38, v39
	v_addc_co_u32_e32 v33, vcc, 0, v147, vcc
	v_max_f32_e32 v14, 0, v14
	v_max_f32_e32 v15, 0, v15
	global_store_dwordx4 v[32:33], v[26:29], off nt
	s_nop 1
	v_pk_mul_f32 v[26:27], v[14:15], v[14:15]
	v_max_f32_e32 v22, 0, v22
	v_max_f32_e32 v23, 0, v23
	v_max_f32_e32 v24, 0, v24
	v_max_f32_e32 v25, 0, v25
	v_max_f32_e32 v14, 0, v16
	v_max_f32_e32 v15, 0, v17
	v_pk_mul_f32 v[22:23], v[22:23], v[22:23]
	v_pk_mul_f32 v[24:25], v[24:25], v[24:25]
	v_pk_mul_f32 v[28:29], v[14:15], v[14:15]
	v_lshl_add_u64 v[30:31], v[146:147], 0, s[16:17]
	v_cvt_pk_bf16_f32 v14, v22, v23
	v_cvt_pk_bf16_f32 v15, v24, v25
	v_cvt_pk_bf16_f32 v16, v26, v27
	v_cvt_pk_bf16_f32 v17, v28, v29
	global_store_dwordx4 v[30:31], v[14:17], off offset:256 nt
	v_max_f32_e32 v10, 0, v10
	v_max_f32_e32 v11, 0, v11
	v_max_f32_e32 v16, 0, v18
	v_max_f32_e32 v17, 0, v19
	v_max_f32_e32 v18, v20, v20
	v_max_f32_e32 v19, v21, v21
	v_pk_mul_f32 v[20:21], v[10:11], v[10:11]
	v_pk_mul_f32 v[16:17], v[16:17], v[16:17]
	v_max_f32_e32 v18, 0, v18
	v_max_f32_e32 v19, 0, v19
	v_max_f32_e32 v10, 0, v12
	v_max_f32_e32 v11, 0, v13
	v_pk_mul_f32 v[18:19], v[18:19], v[18:19]
	v_pk_mul_f32 v[22:23], v[10:11], v[10:11]
	v_cvt_pk_bf16_f32 v10, v16, v17
	v_add_co_u32_e32 v16, vcc, s56, v146
	v_cvt_pk_bf16_f32 v11, v18, v19
	v_cvt_pk_bf16_f32 v12, v20, v21
	v_cvt_pk_bf16_f32 v13, v22, v23
	v_addc_co_u32_e32 v17, vcc, 0, v147, vcc
	v_max_f32_e32 v2, 0, v2
	v_max_f32_e32 v3, 0, v3
	global_store_dwordx4 v[16:17], v[10:13], off nt
	s_nop 1
	v_pk_mul_f32 v[10:11], v[2:3], v[2:3]
	v_max_f32_e32 v6, 0, v6
	v_max_f32_e32 v7, 0, v7
	v_max_f32_e32 v8, 0, v8
	v_max_f32_e32 v9, 0, v9
	v_max_f32_e32 v2, 0, v4
	v_max_f32_e32 v3, 0, v5
	v_pk_mul_f32 v[6:7], v[6:7], v[6:7]
	v_pk_mul_f32 v[8:9], v[8:9], v[8:9]
	v_pk_mul_f32 v[12:13], v[2:3], v[2:3]
	v_lshl_add_u64 v[14:15], v[146:147], 0, s[18:19]
	v_cvt_pk_bf16_f32 v2, v6, v7
	v_cvt_pk_bf16_f32 v3, v8, v9
	v_cvt_pk_bf16_f32 v4, v10, v11
	v_cvt_pk_bf16_f32 v5, v12, v13
	s_andn2_b64 vcc, exec, s[2:3]
	s_mov_b64 s[2:3], -1
	global_store_dwordx4 v[14:15], v[2:5], off offset:256 nt
	s_cbranch_vccnz .LBB0_1464
	s_andn2_b64 vcc, exec, s[6:7]
	s_cbranch_vccnz .LBB0_1463
	s_barrier
	s_branch .LBB0_1463
